# retention loop: software L2 prefetch of tile t+2 via masked LDS-DMA dword touches, tile-end wait vmcnt(8)
# baseline (speedup 1.0000x reference)
.LBB0_803:
	s_nop 6
	v_mul_f32_e32 v71, v79, v188
	v_cvt_pk_bf16_f32 v64, v174, v175
	v_cvt_pk_bf16_f32 v65, v176, v177
	v_cvt_pk_bf16_f32 v66, v178, v179
	v_cvt_pk_bf16_f32 v67, v180, v181
	v_add_u32_e32 v175, s37, v217
	v_cvt_pk_bf16_f32 v68, v182, v183
	v_cvt_pk_bf16_f32 v69, v184, v185
	v_cvt_pk_bf16_f32 v70, v186, v187
	v_cvt_pk_bf16_f32 v71, v194, v71
	ds_write_b128 v175, v[64:67]
	ds_write_b128 v175, v[68:71] offset:1024
	v_add_u32_e32 v224, s0, v202
	v_add_u32_e32 v224, v224, v213
	v_add_u32_e32 v224, 0x8000, v224
	v_xor_b32_e32 v225, s28, v224
	ds_read_b128 v[228:231], v225
	ds_read_b128 v[232:235], v225 offset:4096
	ds_read_b128 v[236:239], v225 offset:8192
	ds_read_b128 v[240:243], v225 offset:12288
	v_xor_b32_e32 v225, s27, v224
	ds_read_b128 v[244:247], v225
	ds_read_b128 v[248:251], v225 offset:4096
	ds_read_b128 v[72:75], v225 offset:8192
	ds_read_b128 v[76:79], v225 offset:12288
	v_add_u32_e32 v174, s56, v217
	s_add_i32 s59, s59, 64
	s_sub_i32 s58, s58, 64
	s_add_u32 s22, s22, 0x80
	s_addc_u32 s23, s23, 0
	s_add_u32 s20, s20, 0xc0000
	s_addc_u32 s21, s21, 0
	s_mov_b32 s63, s61
	s_mov_b32 s62, s60
	s_cmpk_eq_i32 s59, 0x11c0
	s_waitcnt lgkmcnt(4)
	v_mfma_f32_32x32x16_bf16 v[48:63], v[228:231], v[64:67], v[48:63]
	v_mfma_f32_32x32x16_bf16 v[32:47], v[232:235], v[64:67], v[32:47]
	v_mfma_f32_32x32x16_bf16 v[16:31], v[236:239], v[64:67], v[16:31]
	v_mfma_f32_32x32x16_bf16 v[0:15], v[240:243], v[64:67], v[0:15]
	s_waitcnt lgkmcnt(0)
	s_barrier
	ds_read_b128 v[176:179], v174
	ds_read_b128 v[180:183], v174 offset:1024
	v_xor_b32_e32 v225, s26, v224
	ds_read_b128 v[228:231], v225
	ds_read_b128 v[232:235], v225 offset:4096
	ds_read_b128 v[236:239], v225 offset:8192
	ds_read_b128 v[240:243], v225 offset:12288
	v_mfma_f32_32x32x16_bf16 v[48:63], v[244:247], v[68:71], v[48:63]
	v_mfma_f32_32x32x16_bf16 v[32:47], v[248:251], v[68:71], v[32:47]
	v_mfma_f32_32x32x16_bf16 v[16:31], v[72:75], v[68:71], v[16:31]
	v_mfma_f32_32x32x16_bf16 v[0:15], v[76:79], v[68:71], v[0:15]
	v_xor_b32_e32 v225, s5, v224
	ds_read_b128 v[244:247], v225
	ds_read_b128 v[248:251], v225 offset:4096
	ds_read_b128 v[72:75], v225 offset:8192
	ds_read_b128 v[76:79], v225 offset:12288
	s_waitcnt lgkmcnt(4)
	v_mfma_f32_32x32x16_bf16 v[48:63], v[228:231], v[176:179], v[48:63]
	v_mfma_f32_32x32x16_bf16 v[32:47], v[232:235], v[176:179], v[32:47]
	v_mfma_f32_32x32x16_bf16 v[16:31], v[236:239], v[176:179], v[16:31]
	v_mfma_f32_32x32x16_bf16 v[0:15], v[240:243], v[176:179], v[0:15]
	s_waitcnt vmcnt(8) lgkmcnt(0)
	s_barrier
	v_mfma_f32_32x32x16_bf16 v[48:63], v[244:247], v[180:183], v[48:63]
	v_mfma_f32_32x32x16_bf16 v[32:47], v[248:251], v[180:183], v[32:47]
	v_mfma_f32_32x32x16_bf16 v[16:31], v[72:75], v[180:183], v[16:31]
	v_mfma_f32_32x32x16_bf16 v[0:15], v[76:79], v[180:183], v[0:15]
	s_cbranch_scc1 .LBB0_817

.LBB0_806:
	s_add_i32 s61, s63, 0x10000
	s_and_b32 s64, s61, 0x10000
	s_add_i32 s64, s36, s64
	v_lshl_add_u64 v[64:65], s[24:25], 0, v[146:147]
	s_mov_b32 m0, s64
	s_nop 0
	global_load_lds_dwordx4 v[64:65], off
	v_lshl_add_u64 v[64:65], s[24:25], 0, v[150:151]
	s_add_i32 m0, s64, 0x400
	s_nop 0
	global_load_lds_dwordx4 v[64:65], off
	v_lshl_add_u64 v[64:65], s[24:25], 0, v[154:155]
	s_add_i32 m0, s64, 0x800
	s_nop 0
	global_load_lds_dwordx4 v[64:65], off
	s_add_i32 m0, s64, 0xc00
	s_add_u32 s0, s6, s0
	v_lshl_add_u64 v[64:65], s[24:25], 0, v[158:159]
	s_addc_u32 s1, s7, s1
	global_load_lds_dwordx4 v[64:65], off
	v_lshl_add_u64 v[64:65], s[0:1], 0, v[148:149]
	s_add_i32 m0, s64, 0x8000
	s_nop 0
	global_load_lds_dwordx4 v[64:65], off
	v_lshl_add_u64 v[64:65], s[0:1], 0, v[152:153]
	s_add_i32 m0, s64, 0x8400
	s_nop 0
	global_load_lds_dwordx4 v[64:65], off
	v_lshl_add_u64 v[64:65], s[0:1], 0, v[156:157]
	s_add_i32 m0, s64, 0x8800
	s_nop 0
	global_load_lds_dwordx4 v[64:65], off
	v_lshl_add_u64 v[64:65], s[0:1], 0, v[160:161]
	s_add_i32 m0, s64, 0x8c00
	s_nop 0
	global_load_lds_dwordx4 v[64:65], off
	s_add_u32 s24, s24, 0xc0000
	s_addc_u32 s25, s25, 0
	s_mov_b32 exec_lo, 0x1010101
	s_mov_b32 exec_hi, 0x1010101
	s_mov_b32 m0, 0x24000
	v_lshl_add_u64 v[64:65], s[24:25], 0, v[146:147]
	global_load_lds_dword v[64:65], off
	v_lshl_add_u64 v[64:65], s[24:25], 0, v[150:151]
	global_load_lds_dword v[64:65], off
	v_lshl_add_u64 v[64:65], s[24:25], 0, v[154:155]
	global_load_lds_dword v[64:65], off
	v_lshl_add_u64 v[64:65], s[24:25], 0, v[158:159]
	global_load_lds_dword v[64:65], off
	v_lshl_add_u64 v[64:65], s[0:1], 0, v[148:149]
	global_load_lds_dword v[64:65], off offset:128
	v_lshl_add_u64 v[64:65], s[0:1], 0, v[152:153]
	global_load_lds_dword v[64:65], off offset:128
	v_lshl_add_u64 v[64:65], s[0:1], 0, v[156:157]
	global_load_lds_dword v[64:65], off offset:128
	v_lshl_add_u64 v[64:65], s[0:1], 0, v[160:161]
	global_load_lds_dword v[64:65], off offset:128
	s_mov_b64 exec, -1
	s_and_b32 s0, s63, 0x10000
	s_add_i32 s0, s29, s0
	v_add3_u32 v164, s0, v215, v216
	v_xor_b32_e32 v68, 32, v164
	ds_read_b128 v[174:177], v68
	v_xor_b32_e32 v68, 64, v164
	ds_read_b128 v[178:181], v68
	v_xor_b32_e32 v68, 0x60, v164
	ds_read_b128 v[64:67], v164
	ds_read_b128 v[182:185], v68
	s_waitcnt lgkmcnt(0)
	v_mfma_f32_32x32x16_bf16 v[64:79], v[64:67], v[142:145], 0
	v_mfma_f32_32x32x16_bf16 v[64:79], v[174:177], v[138:141], v[64:79]
	v_xor_b32_e32 v165, 0x80, v164
	ds_read_b128 v[174:177], v165
	v_xor_b32_e32 v165, 0xa0, v164
	ds_read_b128 v[224:227], v165
	v_mfma_f32_32x32x16_bf16 v[64:79], v[178:181], v[134:137], v[64:79]
	v_mfma_f32_32x32x16_bf16 v[64:79], v[182:185], v[130:133], v[64:79]
	v_xor_b32_e32 v165, 0xc0, v164
	ds_read_b128 v[178:181], v165
	v_xor_b32_e32 v165, 0xe0, v164
	ds_read_b128 v[182:185], v165
	s_waitcnt lgkmcnt(0)
	v_mfma_f32_32x32x16_bf16 v[64:79], v[174:177], v[126:129], v[64:79]
	v_mfma_f32_32x32x16_bf16 v[64:79], v[224:227], v[122:125], v[64:79]
	v_xor_b32_e32 v165, 0x100, v164
	ds_read_b128 v[174:177], v165
	v_xor_b32_e32 v165, 0x120, v164
	ds_read_b128 v[224:227], v165
	v_mfma_f32_32x32x16_bf16 v[64:79], v[178:181], v[118:121], v[64:79]
	v_mfma_f32_32x32x16_bf16 v[64:79], v[182:185], v[114:117], v[64:79]
	v_xor_b32_e32 v165, 0x140, v164
	ds_read_b128 v[178:181], v165
	v_xor_b32_e32 v165, 0x160, v164
	ds_read_b128 v[182:185], v165
	s_waitcnt lgkmcnt(0)
	v_mfma_f32_32x32x16_bf16 v[64:79], v[174:177], v[108:111], v[64:79]
	v_mfma_f32_32x32x16_bf16 v[64:79], v[224:227], v[104:107], v[64:79]
	v_xor_b32_e32 v165, 0x180, v164
	ds_read_b128 v[174:177], v165
	v_xor_b32_e32 v165, 0x1a0, v164
	ds_read_b128 v[224:227], v165
	v_mfma_f32_32x32x16_bf16 v[64:79], v[178:181], v[100:103], v[64:79]
	v_mfma_f32_32x32x16_bf16 v[64:79], v[182:185], v[96:99], v[64:79]
	v_xor_b32_e32 v165, 0x1c0, v164
	v_xor_b32_e32 v164, 0x1e0, v164
	ds_read_b128 v[178:181], v165
	ds_read_b128 v[182:185], v164
	s_waitcnt lgkmcnt(0)
	v_mfma_f32_32x32x16_bf16 v[64:79], v[174:177], v[92:95], v[64:79]
	v_mfma_f32_32x32x16_bf16 v[64:79], v[224:227], v[88:91], v[64:79]
	v_mfma_f32_32x32x16_bf16 v[64:79], v[178:181], v[84:87], v[64:79]
	v_mfma_f32_32x32x16_bf16 v[64:79], v[182:185], v[80:83], v[64:79]
	s_cmpk_gt_u32 s59, 0xfff
	s_mov_b64 s[24:25], -1
	s_cbranch_scc0 .LBB0_808
	s_and_b32 s1, s62, 0x1fffffc
	s_cmp_eq_u32 s1, 64
	s_cselect_b64 vcc, -1, 0
	v_cndmask_b32_e32 v164, v214, v218, vcc
	v_exp_f32_e32 v188, v164
	s_mov_b64 s[24:25], 0
	s_nop 2
	v_pk_mul_f32 v[174:175], v[188:189], v[64:65] op_sel_hi:[0,1]
	v_pk_mul_f32 v[176:177], v[188:189], v[66:67] op_sel_hi:[0,1]
	v_pk_mul_f32 v[178:179], v[188:189], v[68:69] op_sel_hi:[0,1]
	v_pk_mul_f32 v[180:181], v[188:189], v[70:71] op_sel_hi:[0,1]
	v_pk_mul_f32 v[182:183], v[188:189], v[72:73] op_sel_hi:[0,1]
	v_pk_mul_f32 v[184:185], v[188:189], v[74:75] op_sel_hi:[0,1]
	v_pk_mul_f32 v[186:187], v[188:189], v[76:77] op_sel_hi:[0,1]
	v_mul_f32_e32 v194, v188, v78
